# v16: mLSTM row-tile 3/2 blocks - row-max and gate LDS reads issued at block top / before V reads with counted lgkmcnt waits (on top of v10)
# speedup vs baseline: 1.0052x; 1.0052x over previous
; #define LAS __attribute__((address_space(3)))
; template <int TT>
; DEV void mlstm_a_wave(LAS char* shm, const LAS char* kbuf, const bf16x8 (&qfr)[8], int fr, int fq, float m_prev, const LAS float* tpj, const LAS float* taj, f32x4 (&nacc)[3]) {
;     constexpr int VT = 67584, VRS = 96, NT = TT + 1;
;     const LAS char* kb = kbuf + fr * 512 + ((fq ^ (fr & 3)) << 4);
;     int xo[4];
; #pragma unroll
;     for (int b_ = 0; b_ < 4; ++b_) xo[b_] = ((b_ ^ (fr >> 2)) << 6);
;     ...
;     f32x4 sacc[NT];
; #pragma unroll
;     for (int jj = 0; jj < NT; ++jj) sacc[jj] = (f32x4){0.f, 0.f, 0.f, 0.f};
;     bf16x8 kf[NT];
; #pragma unroll
;     for (int jj = 0; jj < NT; ++jj) kf[jj] = *(const LAS bf16x8*)MLK_ADDR(jj, 0);
; #pragma unroll
;     for (int ks = 0; ks < 8; ++ks) {
;         bf16x8 kn[NT];
; #pragma unroll
;         for (int jj = 0; jj < NT; ++jj) kn[jj] = kf[jj];
;         if (ks < 7) {
; #pragma unroll
;             for (int jj = 0; jj < NT; ++jj) kn[jj] = *(const LAS bf16x8*)MLK_ADDR(jj, ks + 1);
;         }
; #pragma unroll
;         for (int jj = 0; jj < NT; ++jj) sacc[jj] = __builtin_amdgcn_mfma_f32_16x16x32_bf16(kf[jj], qfr[ks], sacc[jj], 0, 0, 0);
; #pragma unroll
;         for (int jj = 0; jj < NT; ++jj) kf[jj] = kn[jj];
;     }
;     ...
;     constexpr int NK = (TT >= 2) ? 2 : 1;
;     s16x4 vlo[NK][3], vhi[NK][3];
; #pragma unroll
;     for (int kk = 0; kk < NK; ++kk)
; #pragma unroll
;         for (int vt = 0; vt < 3; ++vt) {
;             vlo[kk][vt] = __builtin_amdgcn_ds_read_tr16_b64_v4i16((LAS s16x4*)(shm + VT + (32 * kk + 4 * fq + (fr >> 2)) * VRS + (16 * vt + 4 * (fr & 3)) * 2));
;             vhi[kk][vt] = __builtin_amdgcn_ds_read_tr16_b64_v4i16((LAS s16x4*)(shm + VT + (32 * kk + 16 + 4 * fq + (fr >> 2)) * VRS + (16 * vt + 4 * (fr & 3)) * 2));
;         }
;     const int t = 16 * TT + fr;
;     const float btm = -fmaxf(m_prev, tpj[t]);
;     f32x4 sm[2 * NK];
; #pragma unroll
;     for (int jj = 0; jj < 2 * NK; ++jj) {
;         if (jj < NT) {
;             const f32x4 a4 = *(const LAS f32x4*)(taj + 16 * jj + 4 * fq);
.LBB0_652:
	s_and_b32 s29, s38, 0x8000
	s_andn2_b64 vcc, exec, s[0:1]
	s_add_i32 s29, s29, 0
	s_cbranch_vccnz .LBB0_664
	v_add3_u32 v5, s29, v180, v181
	v_add_u32_e32 v4, v5, v182
	ds_read_b128 v[110:113], v4
	s_cmp_lt_i32 s67, 2
	s_mov_b64 s[0:1], -1
	s_cbranch_scc1 .LBB0_659
	s_cmp_gt_i32 s67, 2
	s_cbranch_scc0 .LBB0_656
	v_add_u32_e32 v239, s40, v203
	v_add_u32_e32 v239, 0x235c0, v239
	ds_read_b32 v238, v239
	v_add_u32_e32 v241, s40, v202
	v_add_u32_e32 v239, 0x21580, v241
	ds_read_b128 v[250:253], v239
	v_add_u32_e32 v239, 0x215c0, v241
	ds_read_b128 v[246:249], v239
	ds_read_b128 v[114:117], v4 offset:8192
	ds_read_b128 v[118:121], v4 offset:16384
	ds_read_b128 v[122:125], v4 offset:24576
	v_add_u32_e32 v0, v5, v183
	ds_read_b128 v[126:129], v0
	ds_read_b128 v[130:133], v0 offset:8192
	ds_read_b128 v[134:137], v0 offset:16384
	ds_read_b128 v[138:141], v0 offset:24576
	s_waitcnt lgkmcnt(4)
	v_mfma_f32_16x16x32_bf16 v[142:145], v[110:113], v[38:41], 0
	v_add_u32_e32 v1, v5, v184
	ds_read_b128 v[146:149], v1
	ds_read_b128 v[150:153], v1 offset:8192
	ds_read_b128 v[230:233], v1 offset:16384
	ds_read_b128 v[234:237], v1 offset:24576
	v_add_u32_e32 v229, v5, v185
	v_mfma_f32_16x16x32_bf16 v[114:117], v[114:117], v[38:41], 0
	s_mov_b64 s[0:1], 0
	v_mfma_f32_16x16x32_bf16 v[118:121], v[118:121], v[38:41], 0
	v_mfma_f32_16x16x32_bf16 v[122:125], v[122:125], v[38:41], 0
	s_waitcnt lgkmcnt(4)
	v_mfma_f32_16x16x32_bf16 v[126:129], v[126:129], v[34:37], v[142:145]
	v_mfma_f32_16x16x32_bf16 v[114:117], v[130:133], v[34:37], v[114:117]
	v_mfma_f32_16x16x32_bf16 v[118:121], v[134:137], v[34:37], v[118:121]
	v_mfma_f32_16x16x32_bf16 v[122:125], v[138:141], v[34:37], v[122:125]
	ds_read_b128 v[130:133], v229
	ds_read_b128 v[134:137], v229 offset:8192
	ds_read_b128 v[138:141], v229 offset:16384
	ds_read_b128 v[142:145], v229 offset:24576
	s_waitcnt lgkmcnt(4)
	v_mfma_f32_16x16x32_bf16 v[126:129], v[146:149], v[30:33], v[126:129]
	v_mfma_f32_16x16x32_bf16 v[114:117], v[150:153], v[30:33], v[114:117]
	v_mfma_f32_16x16x32_bf16 v[118:121], v[230:233], v[30:33], v[118:121]
	v_mfma_f32_16x16x32_bf16 v[122:125], v[234:237], v[30:33], v[122:125]
	ds_read_b128 v[146:149], v4 offset:256
	ds_read_b128 v[150:153], v4 offset:8448
	ds_read_b128 v[230:233], v4 offset:16640
	ds_read_b128 v[234:237], v4 offset:24832
	s_waitcnt lgkmcnt(4)
	v_mfma_f32_16x16x32_bf16 v[126:129], v[130:133], v[10:13], v[126:129]
	v_mfma_f32_16x16x32_bf16 v[114:117], v[134:137], v[10:13], v[114:117]
	v_mfma_f32_16x16x32_bf16 v[118:121], v[138:141], v[10:13], v[118:121]
	v_mfma_f32_16x16x32_bf16 v[122:125], v[142:145], v[10:13], v[122:125]
	ds_read_b128 v[130:133], v0 offset:256
	ds_read_b128 v[134:137], v0 offset:8448
	ds_read_b128 v[138:141], v0 offset:16640
	ds_read_b128 v[142:145], v0 offset:24832
	v_add_u32_e32 v0, v187, v186
	s_waitcnt lgkmcnt(4)
	v_mfma_f32_16x16x32_bf16 v[126:129], v[146:149], v[26:29], v[126:129]
	v_mfma_f32_16x16x32_bf16 v[114:117], v[150:153], v[26:29], v[114:117]
	v_mfma_f32_16x16x32_bf16 v[118:121], v[230:233], v[26:29], v[118:121]
	v_mfma_f32_16x16x32_bf16 v[122:125], v[234:237], v[26:29], v[122:125]
	ds_read_b128 v[146:149], v1 offset:256
	ds_read_b128 v[150:153], v1 offset:8448
	ds_read_b128 v[230:233], v1 offset:16640
	ds_read_b128 v[234:237], v1 offset:24832
	s_waitcnt lgkmcnt(4)
	v_mfma_f32_16x16x32_bf16 v[126:129], v[130:133], v[22:25], v[126:129]
	v_mfma_f32_16x16x32_bf16 v[114:117], v[134:137], v[22:25], v[114:117]
	v_mfma_f32_16x16x32_bf16 v[118:121], v[138:141], v[22:25], v[118:121]
	ds_read_b128 v[130:133], v229 offset:256
	ds_read_b128 v[134:137], v229 offset:8448
	ds_read_b128 v[138:141], v229 offset:16640
	ds_read_b128 v[242:245], v229 offset:24832
	v_mfma_f32_16x16x32_bf16 v[122:125], v[142:145], v[22:25], v[122:125]
	s_waitcnt lgkmcnt(4)
	v_mfma_f32_16x16x32_bf16 v[126:129], v[146:149], v[14:17], v[126:129]
	v_mfma_f32_16x16x32_bf16 v[114:117], v[150:153], v[14:17], v[114:117]
	v_mfma_f32_16x16x32_bf16 v[118:121], v[230:233], v[14:17], v[118:121]
	v_mfma_f32_16x16x32_bf16 v[122:125], v[234:237], v[14:17], v[122:125]
	s_waitcnt lgkmcnt(0)
	v_mfma_f32_16x16x32_bf16 v[130:133], v[130:133], v[18:21], v[126:129]
	v_mfma_f32_16x16x32_bf16 v[142:145], v[134:137], v[18:21], v[114:117]
	v_mfma_f32_16x16x32_bf16 v[146:149], v[138:141], v[18:21], v[118:121]
	v_mfma_f32_16x16x32_bf16 v[230:233], v[242:245], v[18:21], v[122:125]
	s_nop 0
	v_add_u32_e32 v1, 0x21500, v241
	ds_read_b128 v[150:153], v1
	v_add_u32_e32 v1, 0x21540, v241
	ds_read_b128 v[234:237], v1
	ds_read_b64_tr_b16 v[140:141], v0 offset:1536
	ds_read_b64_tr_b16 v[138:139], v0
	ds_read_b64_tr_b16 v[134:135], v0 offset:32
	ds_read_b64_tr_b16 v[136:137], v0 offset:1568
	ds_read_b64_tr_b16 v[126:127], v0 offset:64
	ds_read_b64_tr_b16 v[128:129], v0 offset:1600
	ds_read_b64_tr_b16 v[118:119], v0 offset:3072
	ds_read_b64_tr_b16 v[120:121], v0 offset:4608
	ds_read_b64_tr_b16 v[114:115], v0 offset:3104
	ds_read_b64_tr_b16 v[116:117], v0 offset:4640
	ds_read_b64_tr_b16 v[122:123], v0 offset:3136
	ds_read_b64_tr_b16 v[124:125], v0 offset:4672
	s_waitcnt lgkmcnt(12)
; DEV unsigned pk2(float lo, float hi) { f32n2 v = {lo, hi}; bf16n2 b = __builtin_convertvector(v, bf16n2); return __builtin_bit_cast(unsigned, b); }
; #define LAS __attribute__((address_space(3)))
; template <int TT>
; DEV void mlstm_a_wave(LAS char* shm, const LAS char* kbuf, const bf16x8 (&qfr)[8], int fr, int fq, float m_prev, const LAS float* tpj, const LAS float* taj, f32x4 (&nacc)[3]) {
;     ...
;     const int t = 16 * TT + fr;
;     const float btm = -fmaxf(m_prev, tpj[t]);
;     f32x4 sm[2 * NK];
; #pragma unroll
;     for (int jj = 0; jj < 2 * NK; ++jj) {
;         if (jj < NT) {
;             const f32x4 a4 = *(const LAS f32x4*)(taj + 16 * jj + 4 * fq);
; #pragma unroll
;             for (int r = 0; r < 4; ++r) {
;                 const int s_ = 16 * jj + 4 * fq + r;
;                 sm[jj][r] = (jj < TT || s_ <= t) ? sacc[jj < NT ? jj : 0][r] * __expf(btm + a4[r]) : 0.f;
;             }
;         } else sm[jj] = (f32x4){0.f, 0.f, 0.f, 0.f};
;     }
; #pragma unroll
;     for (int kk = 0; kk < NK; ++kk) {
;         const u32x4 u = (u32x4){pk2(sm[2 * kk][0], sm[2 * kk][1]), pk2(sm[2 * kk][2], sm[2 * kk][3]), pk2(sm[2 * kk + 1][0], sm[2 * kk + 1][1]), pk2(sm[2 * kk + 1][2], sm[2 * kk + 1][3])};
;         const bf16x8 af = *(const bf16x8*)&u;
; #pragma unroll
;         for (int vt = 0; vt < 3; ++vt) {
;             bf16x8 bv8; bv8[0] = vlo[kk][vt][0]; bv8[1] = vlo[kk][vt][1]; bv8[2] = vlo[kk][vt][2]; bv8[3] = vlo[kk][vt][3];
;             bv8[4] = vhi[kk][vt][0]; bv8[5] = vhi[kk][vt][1]; bv8[6] = vhi[kk][vt][2]; bv8[7] = vhi[kk][vt][3];
;             nacc[vt] = __builtin_amdgcn_mfma_f32_16x16x32_bf16(af, bv8, nacc[vt], 0, 0, 0);
;         }
;     }
	v_max_f32_e32 v0, v238, v238
	v_max_f32_e32 v229, v227, v0
	s_nop 0
	v_sub_f32_e32 v1, v251, v229
	s_nop 0
	v_sub_f32_e32 v0, v246, v229
	v_mul_f32_e32 v0, 0x3fb8aa3b, v0
	v_exp_f32_e32 v0, v0
	v_mul_f32_e32 v1, 0x3fb8aa3b, v1
	v_exp_f32_e32 v1, v1
	v_mul_f32_e32 v0, v230, v0
	v_cndmask_b32_e64 v230, v0, 0, s[6:7]
	v_sub_f32_e32 v0, v247, v229
	v_mul_f32_e32 v0, 0x3fb8aa3b, v0
	v_exp_f32_e32 v0, v0
	s_nop 0
	v_mul_f32_e32 v0, v231, v0
	v_cndmask_b32_e64 v231, 0, v0, s[8:9]
	v_sub_f32_e32 v0, v248, v229
	v_mul_f32_e32 v0, 0x3fb8aa3b, v0
	v_exp_f32_e32 v0, v0
	s_nop 0
	v_mul_f32_e32 v0, v232, v0
	v_cndmask_b32_e64 v232, v0, 0, s[10:11]
	v_sub_f32_e32 v0, v249, v229
	v_mul_f32_e32 v0, 0x3fb8aa3b, v0
	v_exp_f32_e32 v0, v0
	s_nop 0
	v_mul_f32_e32 v0, v233, v0
	v_cndmask_b32_e64 v233, v0, 0, s[12:13]
	v_sub_f32_e32 v0, v250, v229
	v_mul_f32_e32 v0, 0x3fb8aa3b, v0
	v_exp_f32_e32 v0, v0
	s_nop 0
	v_pk_mul_f32 v[0:1], v[146:147], v[0:1]
	v_sub_f32_e32 v146, v252, v229
	v_sub_f32_e32 v147, v253, v229
	v_mul_f32_e32 v146, 0x3fb8aa3b, v146
	v_mul_f32_e32 v147, 0x3fb8aa3b, v147
	v_exp_f32_e32 v146, v146
	v_exp_f32_e32 v147, v147
	s_nop 0
	v_pk_mul_f32 v[146:147], v[148:149], v[146:147]
	v_sub_f32_e32 v148, v234, v229
	v_sub_f32_e32 v149, v235, v229
	v_mul_f32_e32 v148, 0x3fb8aa3b, v148
	v_mul_f32_e32 v149, 0x3fb8aa3b, v149
	v_exp_f32_e32 v148, v148
	v_exp_f32_e32 v149, v149
	s_nop 0
	v_pk_mul_f32 v[142:143], v[142:143], v[148:149]
	v_sub_f32_e32 v148, v236, v229
	v_sub_f32_e32 v149, v237, v229
	v_mul_f32_e32 v148, 0x3fb8aa3b, v148
	v_mul_f32_e32 v149, 0x3fb8aa3b, v149
	v_exp_f32_e32 v148, v148
	v_exp_f32_e32 v149, v149
	s_nop 0
	v_pk_mul_f32 v[144:145], v[144:145], v[148:149]
	v_sub_f32_e32 v148, v150, v229
	v_sub_f32_e32 v149, v151, v229
	v_mul_f32_e32 v148, 0x3fb8aa3b, v148
	v_mul_f32_e32 v149, 0x3fb8aa3b, v149
	v_exp_f32_e32 v148, v148
	v_exp_f32_e32 v149, v149
	s_nop 0
	v_pk_mul_f32 v[130:131], v[130:131], v[148:149]
	v_sub_f32_e32 v148, v152, v229
	v_sub_f32_e32 v149, v153, v229
	v_mul_f32_e32 v148, 0x3fb8aa3b, v148
	v_mul_f32_e32 v149, 0x3fb8aa3b, v149
	v_exp_f32_e32 v148, v148
	v_exp_f32_e32 v149, v149
	v_cvt_pk_bf16_f32 v130, v130, v131
	v_pk_mul_f32 v[132:133], v[132:133], v[148:149]
	s_nop 0
	v_cvt_pk_bf16_f32 v131, v132, v133
	v_cvt_pk_bf16_f32 v132, v142, v143
	v_cvt_pk_bf16_f32 v133, v144, v145
	s_waitcnt lgkmcnt(0)
	s_nop 1
	v_mfma_f32_16x16x32_bf16 v[138:141], v[130:133], v[138:141], 0
	v_mfma_f32_16x16x32_bf16 v[134:137], v[130:133], v[134:137], 0
	v_mfma_f32_16x16x32_bf16 v[126:129], v[130:133], v[126:129], 0
	v_cvt_pk_bf16_f32 v130, v0, v1
	v_cvt_pk_bf16_f32 v131, v146, v147
	v_cvt_pk_bf16_f32 v132, v230, v231
	v_cvt_pk_bf16_f32 v133, v232, v233
	s_nop 1
	v_mfma_f32_16x16x32_bf16 v[118:121], v[130:133], v[118:121], v[138:141]
	v_mfma_f32_16x16x32_bf16 v[114:117], v[130:133], v[114:117], v[134:137]
	v_mfma_f32_16x16x32_bf16 v[122:125], v[130:133], v[122:125], v[126:129]
; template <int TT>
; DEV void mlstm_a_wave(LAS char* shm, const LAS char* kbuf, const bf16x8 (&qfr)[8], int fr, int fq, float m_prev, const LAS float* tpj, const LAS float* taj, f32x4 (&nacc)[3]) {
;     constexpr int VT = 67584, VRS = 96, NT = TT + 1;
;     const LAS char* kb = kbuf + fr * 512 + ((fq ^ (fr & 3)) << 4);
;     int xo[4];
; #pragma unroll
;     for (int b_ = 0; b_ < 4; ++b_) xo[b_] = ((b_ ^ (fr >> 2)) << 6);
;     ...
;     f32x4 sacc[NT];
; #pragma unroll
;     for (int jj = 0; jj < NT; ++jj) sacc[jj] = (f32x4){0.f, 0.f, 0.f, 0.f};
;     bf16x8 kf[NT];
; #pragma unroll
;     for (int jj = 0; jj < NT; ++jj) kf[jj] = *(const LAS bf16x8*)MLK_ADDR(jj, 0);
; #pragma unroll
;     for (int ks = 0; ks < 8; ++ks) {
;         bf16x8 kn[NT];
; #pragma unroll
;         for (int jj = 0; jj < NT; ++jj) kn[jj] = kf[jj];
;         if (ks < 7) {
; #pragma unroll
;             for (int jj = 0; jj < NT; ++jj) kn[jj] = *(const LAS bf16x8*)MLK_ADDR(jj, ks + 1);
;         }
; #pragma unroll
;         for (int jj = 0; jj < NT; ++jj) sacc[jj] = __builtin_amdgcn_mfma_f32_16x16x32_bf16(kf[jj], qfr[ks], sacc[jj], 0, 0, 0);
; #pragma unroll
;         for (int jj = 0; jj < NT; ++jj) kf[jj] = kn[jj];
;     }
;     ...
;     constexpr int NK = (TT >= 2) ? 2 : 1;
;     s16x4 vlo[NK][3], vhi[NK][3];
; #pragma unroll
;     for (int kk = 0; kk < NK; ++kk)
; #pragma unroll
;         for (int vt = 0; vt < 3; ++vt) {
;             vlo[kk][vt] = __builtin_amdgcn_ds_read_tr16_b64_v4i16((LAS s16x4*)(shm + VT + (32 * kk + 4 * fq + (fr >> 2)) * VRS + (16 * vt + 4 * (fr & 3)) * 2));
;             vhi[kk][vt] = __builtin_amdgcn_ds_read_tr16_b64_v4i16((LAS s16x4*)(shm + VT + (32 * kk + 16 + 4 * fq + (fr >> 2)) * VRS + (16 * vt + 4 * (fr & 3)) * 2));
;         }
;     const int t = 16 * TT + fr;
;     const float btm = -fmaxf(m_prev, tpj[t]);
;     f32x4 sm[2 * NK];
; #pragma unroll
;     for (int jj = 0; jj < 2 * NK; ++jj) {
;         if (jj < NT) {
;             const f32x4 a4 = *(const LAS f32x4*)(taj + 16 * jj + 4 * fq);
; #pragma unroll
;             for (int r = 0; r < 4; ++r) {
;                 const int s_ = 16 * jj + 4 * fq + r;
;                 sm[jj][r] = (jj < TT || s_ <= t) ? sacc[jj < NT ? jj : 0][r] * __expf(btm + a4[r]) : 0.f;
;             }
;         } else sm[jj] = (f32x4){0.f, 0.f, 0.f, 0.f};
;     }
; #pragma unroll
;     for (int kk = 0; kk < NK; ++kk) {
.LBB0_656:
	s_andn2_b64 vcc, exec, s[0:1]
	s_cbranch_vccnz .LBB0_658
	s_nop 4
	v_add_u32_e32 v239, s40, v203
	v_add_u32_e32 v239, 0x23580, v239
	ds_read_b32 v238, v239
	v_add_u32_e32 v241, s40, v202
	v_add_u32_e32 v239, 0x21500, v241
	ds_read_b128 v[250:253], v239
	v_add_u32_e32 v239, 0x21540, v241
	ds_read_b128 v[230:233], v239
	v_add_u32_e32 v239, 0x21580, v241
	ds_read_b128 v[234:237], v239
	ds_read_b128 v[114:117], v4 offset:8192
	ds_read_b128 v[118:121], v4 offset:16384
	v_add_u32_e32 v0, v5, v183
	ds_read_b128 v[122:125], v0
	ds_read_b128 v[126:129], v0 offset:8192
	ds_read_b128 v[130:133], v0 offset:16384
	s_waitcnt lgkmcnt(3)
	v_mfma_f32_16x16x32_bf16 v[134:137], v[110:113], v[38:41], 0
	v_add_u32_e32 v1, v5, v184
	ds_read_b128 v[138:141], v1
	ds_read_b128 v[142:145], v1 offset:8192
	ds_read_b128 v[146:149], v1 offset:16384
	v_add_u32_e32 v150, v5, v185
	v_mfma_f32_16x16x32_bf16 v[114:117], v[114:117], v[38:41], 0
	v_mfma_f32_16x16x32_bf16 v[118:121], v[118:121], v[38:41], 0
	s_waitcnt lgkmcnt(3)
	v_mfma_f32_16x16x32_bf16 v[122:125], v[122:125], v[34:37], v[134:137]
	v_mfma_f32_16x16x32_bf16 v[114:117], v[126:129], v[34:37], v[114:117]
	v_mfma_f32_16x16x32_bf16 v[118:121], v[130:133], v[34:37], v[118:121]
	ds_read_b128 v[126:129], v150
	ds_read_b128 v[130:133], v150 offset:8192
	ds_read_b128 v[134:137], v150 offset:16384
	s_waitcnt lgkmcnt(3)
	v_mfma_f32_16x16x32_bf16 v[122:125], v[138:141], v[30:33], v[122:125]
	v_mfma_f32_16x16x32_bf16 v[114:117], v[142:145], v[30:33], v[114:117]
	v_mfma_f32_16x16x32_bf16 v[118:121], v[146:149], v[30:33], v[118:121]
	ds_read_b128 v[138:141], v4 offset:256
	ds_read_b128 v[142:145], v4 offset:8448
	ds_read_b128 v[146:149], v4 offset:16640
	s_waitcnt lgkmcnt(3)
	v_mfma_f32_16x16x32_bf16 v[122:125], v[126:129], v[10:13], v[122:125]
	v_mfma_f32_16x16x32_bf16 v[114:117], v[130:133], v[10:13], v[114:117]
	v_mfma_f32_16x16x32_bf16 v[118:121], v[134:137], v[10:13], v[118:121]
	ds_read_b128 v[126:129], v0 offset:256
	ds_read_b128 v[130:133], v0 offset:8448
	ds_read_b128 v[134:137], v0 offset:16640
	v_add_u32_e32 v0, v187, v186
	s_waitcnt lgkmcnt(3)
	v_mfma_f32_16x16x32_bf16 v[122:125], v[138:141], v[26:29], v[122:125]
	v_mfma_f32_16x16x32_bf16 v[114:117], v[142:145], v[26:29], v[114:117]
	v_mfma_f32_16x16x32_bf16 v[118:121], v[146:149], v[26:29], v[118:121]
	ds_read_b128 v[138:141], v1 offset:256
	ds_read_b128 v[142:145], v1 offset:8448
	ds_read_b128 v[146:149], v1 offset:16640
	s_waitcnt lgkmcnt(3)
	v_mfma_f32_16x16x32_bf16 v[122:125], v[126:129], v[22:25], v[122:125]
	v_mfma_f32_16x16x32_bf16 v[114:117], v[130:133], v[22:25], v[114:117]
	v_mfma_f32_16x16x32_bf16 v[118:121], v[134:137], v[22:25], v[118:121]
	ds_read_b128 v[126:129], v150 offset:256
	ds_read_b128 v[130:133], v150 offset:8448
	ds_read_b128 v[134:137], v150 offset:16640
	s_waitcnt lgkmcnt(3)
	v_mfma_f32_16x16x32_bf16 v[122:125], v[138:141], v[14:17], v[122:125]
	v_mfma_f32_16x16x32_bf16 v[114:117], v[142:145], v[14:17], v[114:117]
	v_mfma_f32_16x16x32_bf16 v[118:121], v[146:149], v[14:17], v[118:121]
	s_waitcnt lgkmcnt(0)
	v_mfma_f32_16x16x32_bf16 v[142:145], v[126:129], v[18:21], v[122:125]
	v_mfma_f32_16x16x32_bf16 v[130:133], v[130:133], v[18:21], v[114:117]
	v_mfma_f32_16x16x32_bf16 v[146:149], v[134:137], v[18:21], v[118:121]
	s_nop 0
	ds_read_b64_tr_b16 v[140:141], v0 offset:1536
	ds_read_b64_tr_b16 v[138:139], v0
	ds_read_b64_tr_b16 v[134:135], v0 offset:32
	ds_read_b64_tr_b16 v[136:137], v0 offset:1568
	ds_read_b64_tr_b16 v[126:127], v0 offset:64
	ds_read_b64_tr_b16 v[128:129], v0 offset:1600
	ds_read_b64_tr_b16 v[118:119], v0 offset:3072
	ds_read_b64_tr_b16 v[120:121], v0 offset:4608
	ds_read_b64_tr_b16 v[114:115], v0 offset:3104
	ds_read_b64_tr_b16 v[116:117], v0 offset:4640
	ds_read_b64_tr_b16 v[122:123], v0 offset:3136
	ds_read_b64_tr_b16 v[124:125], v0 offset:4672
	s_waitcnt lgkmcnt(12)
	v_max_f32_e32 v0, v238, v238
	v_max_f32_e32 v229, v227, v0
	s_nop 0
	v_sub_f32_e32 v0, v234, v229
	v_mul_f32_e32 v0, 0x3fb8aa3b, v0
	v_exp_f32_e32 v0, v0
	v_sub_f32_e32 v1, v237, v229
	v_mul_f32_e32 v1, 0x3fb8aa3b, v1
	v_exp_f32_e32 v1, v1
	v_mul_f32_e32 v0, v146, v0
	v_cndmask_b32_e64 v234, v0, 0, s[6:7]
	v_sub_f32_e32 v0, v235, v229
	v_mul_f32_e32 v0, 0x3fb8aa3b, v0
	v_exp_f32_e32 v0, v0
	v_sub_f32_e32 v146, v250, v229
	v_mul_f32_e32 v146, 0x3fb8aa3b, v146
	v_exp_f32_e32 v146, v146
	v_mul_f32_e32 v0, v147, v0
	v_sub_f32_e32 v147, v251, v229
	v_mul_f32_e32 v147, 0x3fb8aa3b, v147
	v_exp_f32_e32 v147, v147
	v_cndmask_b32_e64 v235, v0, 0, s[14:15]
	v_sub_f32_e32 v0, v236, v229
	v_mul_f32_e32 v0, 0x3fb8aa3b, v0
	v_pk_mul_f32 v[142:143], v[142:143], v[146:147]
	v_sub_f32_e32 v146, v252, v229
	v_sub_f32_e32 v147, v253, v229
	v_mul_f32_e32 v146, 0x3fb8aa3b, v146
	v_mul_f32_e32 v147, 0x3fb8aa3b, v147
	v_exp_f32_e32 v146, v146
	v_exp_f32_e32 v147, v147
	v_exp_f32_e32 v0, v0
	v_pk_mul_f32 v[144:145], v[144:145], v[146:147]
	v_sub_f32_e32 v146, v230, v229
	v_sub_f32_e32 v147, v231, v229
	v_mul_f32_e32 v146, 0x3fb8aa3b, v146
	v_mul_f32_e32 v147, 0x3fb8aa3b, v147
	v_exp_f32_e32 v146, v146
	v_exp_f32_e32 v147, v147
	v_pk_mul_f32 v[0:1], v[148:149], v[0:1]
	v_pk_mul_f32 v[146:147], v[130:131], v[146:147]
	v_sub_f32_e32 v130, v232, v229
	v_sub_f32_e32 v131, v233, v229
	v_mul_f32_e32 v130, 0x3fb8aa3b, v130
	v_mul_f32_e32 v131, 0x3fb8aa3b, v131
	v_exp_f32_e32 v130, v130
	v_exp_f32_e32 v131, v131
	v_cvt_pk_bf16_f32 v0, v0, v1
	v_cndmask_b32_e64 v1, v0, 0, s[18:19]
	v_lshrrev_b32_e32 v0, 16, v0
	v_pk_mul_f32 v[148:149], v[132:133], v[130:131]
	v_cvt_pk_bf16_f32 v130, v142, v143
	v_cvt_pk_bf16_f32 v131, v144, v145
	v_cvt_pk_bf16_f32 v132, v146, v147
	v_cvt_pk_bf16_f32 v133, v148, v149
	v_cndmask_b32_e64 v0, v0, 0, s[16:17]
	s_waitcnt lgkmcnt(0)
	s_nop 0
	v_mfma_f32_16x16x32_bf16 v[138:141], v[130:133], v[138:141], 0
	v_mfma_f32_16x16x32_bf16 v[134:137], v[130:133], v[134:137], 0
	v_mfma_f32_16x16x32_bf16 v[126:129], v[130:133], v[126:129], 0
	v_cvt_pk_bf16_f32 v130, v234, v235
	v_perm_b32 v131, v0, v1, s60
	v_mov_b32_e32 v132, v3
	v_mov_b32_e32 v133, v3
	s_nop 1
	v_mfma_f32_16x16x32_bf16 v[118:121], v[130:133], v[118:121], v[138:141]
	v_mfma_f32_16x16x32_bf16 v[114:117], v[130:133], v[114:117], v[134:137]
	v_mfma_f32_16x16x32_bf16 v[122:125], v[130:133], v[122:125], v[126:129]

; #define LAS __attribute__((address_space(3)))
; template <int TT>
; DEV void mlstm_a_wave(LAS char* shm, const LAS char* kbuf, const bf16x8 (&qfr)[8], int fr, int fq, float m_prev, const LAS float* tpj, const LAS float* taj, f32x4 (&nacc)[3]) {
;     constexpr int VT = 67584, VRS = 96, NT = TT + 1;
;     const LAS char* kb = kbuf + fr * 512 + ((fq ^ (fr & 3)) << 4);
;     int xo[4];
; #pragma unroll
;     for (int b_ = 0; b_ < 4; ++b_) xo[b_] = ((b_ ^ (fr >> 2)) << 6);
;     ...
;     f32x4 sacc[NT];
; #pragma unroll
;     for (int jj = 0; jj < NT; ++jj) sacc[jj] = (f32x4){0.f, 0.f, 0.f, 0.f};
;     bf16x8 kf[NT];
; #pragma unroll
;     for (int jj = 0; jj < NT; ++jj) kf[jj] = *(const LAS bf16x8*)MLK_ADDR(jj, 0);
; #pragma unroll
;     for (int ks = 0; ks < 8; ++ks) {
;         bf16x8 kn[NT];
; #pragma unroll
;         for (int jj = 0; jj < NT; ++jj) kn[jj] = kf[jj];
;         if (ks < 7) {
; #pragma unroll
;             for (int jj = 0; jj < NT; ++jj) kn[jj] = *(const LAS bf16x8*)MLK_ADDR(jj, ks + 1);
;         }
; #pragma unroll
;         for (int jj = 0; jj < NT; ++jj) sacc[jj] = __builtin_amdgcn_mfma_f32_16x16x32_bf16(kf[jj], qfr[ks], sacc[jj], 0, 0, 0);
; #pragma unroll
;         for (int jj = 0; jj < NT; ++jj) kf[jj] = kn[jj];
;     }
;     ...
;     constexpr int NK = (TT >= 2) ? 2 : 1;
;     s16x4 vlo[NK][3], vhi[NK][3];
; #pragma unroll
;     for (int kk = 0; kk < NK; ++kk)
; #pragma unroll
;         for (int vt = 0; vt < 3; ++vt) {
;             vlo[kk][vt] = __builtin_amdgcn_ds_read_tr16_b64_v4i16((LAS s16x4*)(shm + VT + (32 * kk + 4 * fq + (fr >> 2)) * VRS + (16 * vt + 4 * (fr & 3)) * 2));
;             vhi[kk][vt] = __builtin_amdgcn_ds_read_tr16_b64_v4i16((LAS s16x4*)(shm + VT + (32 * kk + 16 + 4 * fq + (fr >> 2)) * VRS + (16 * vt + 4 * (fr & 3)) * 2));
;         }
;     const int t = 16 * TT + fr;
;     const float btm = -fmaxf(m_prev, tpj[t]);
;     f32x4 sm[2 * NK];
; #pragma unroll
;     for (int jj = 0; jj < 2 * NK; ++jj) {
;         if (jj < NT) {
;             const f32x4 a4 = *(const LAS f32x4*)(taj + 16 * jj + 4 * fq);
.LBB0_1503:
	s_and_b32 s29, s38, 0x8000
	s_andn2_b64 vcc, exec, s[0:1]
	s_add_i32 s29, s29, 0
	s_cbranch_vccnz .LBB0_1515
	v_add3_u32 v5, s29, v180, v181
	v_add_u32_e32 v4, v5, v182
	ds_read_b128 v[110:113], v4
	s_cmp_lt_i32 s61, 2
	s_mov_b64 s[0:1], -1
	s_cbranch_scc1 .LBB0_1510
	s_cmp_gt_i32 s61, 2
	s_cbranch_scc0 .LBB0_1507
	v_add_u32_e32 v247, s40, v203
	v_add_u32_e32 v247, 0x235c0, v247
	ds_read_b32 v246, v247
	v_add_u32_e32 v252, s40, v202
	v_add_u32_e32 v247, 0x21580, v252
	ds_read_b128 v[248:251], v247
	v_add_u32_e32 v247, 0x215c0, v252
	ds_read_b128 v[242:245], v247
	ds_read_b128 v[114:117], v4 offset:8192
	ds_read_b128 v[118:121], v4 offset:16384
	ds_read_b128 v[122:125], v4 offset:24576
	v_add_u32_e32 v0, v5, v183
	ds_read_b128 v[126:129], v0
	ds_read_b128 v[130:133], v0 offset:8192
	ds_read_b128 v[134:137], v0 offset:16384
	ds_read_b128 v[138:141], v0 offset:24576
	s_waitcnt lgkmcnt(4)
	v_mfma_f32_16x16x32_bf16 v[142:145], v[110:113], v[38:41], 0
	v_add_u32_e32 v1, v5, v184
	ds_read_b128 v[146:149], v1
	ds_read_b128 v[150:153], v1 offset:8192
	ds_read_b128 v[230:233], v1 offset:16384
	ds_read_b128 v[234:237], v1 offset:24576
	v_add_u32_e32 v229, v5, v185
	v_mfma_f32_16x16x32_bf16 v[114:117], v[114:117], v[38:41], 0
	s_mov_b64 s[0:1], 0
	v_mfma_f32_16x16x32_bf16 v[118:121], v[118:121], v[38:41], 0
	v_mfma_f32_16x16x32_bf16 v[122:125], v[122:125], v[38:41], 0
	s_waitcnt lgkmcnt(4)
	v_mfma_f32_16x16x32_bf16 v[126:129], v[126:129], v[34:37], v[142:145]
	v_mfma_f32_16x16x32_bf16 v[114:117], v[130:133], v[34:37], v[114:117]
	v_mfma_f32_16x16x32_bf16 v[118:121], v[134:137], v[34:37], v[118:121]
	v_mfma_f32_16x16x32_bf16 v[122:125], v[138:141], v[34:37], v[122:125]
	ds_read_b128 v[130:133], v229
	ds_read_b128 v[134:137], v229 offset:8192
	ds_read_b128 v[138:141], v229 offset:16384
	ds_read_b128 v[142:145], v229 offset:24576
	s_waitcnt lgkmcnt(4)
	v_mfma_f32_16x16x32_bf16 v[126:129], v[146:149], v[30:33], v[126:129]
	v_mfma_f32_16x16x32_bf16 v[114:117], v[150:153], v[30:33], v[114:117]
	v_mfma_f32_16x16x32_bf16 v[118:121], v[230:233], v[30:33], v[118:121]
	v_mfma_f32_16x16x32_bf16 v[122:125], v[234:237], v[30:33], v[122:125]
	ds_read_b128 v[146:149], v4 offset:256
	ds_read_b128 v[150:153], v4 offset:8448
	ds_read_b128 v[230:233], v4 offset:16640
	ds_read_b128 v[234:237], v4 offset:24832
	s_waitcnt lgkmcnt(4)
	v_mfma_f32_16x16x32_bf16 v[126:129], v[130:133], v[10:13], v[126:129]
	v_mfma_f32_16x16x32_bf16 v[114:117], v[134:137], v[10:13], v[114:117]
	v_mfma_f32_16x16x32_bf16 v[118:121], v[138:141], v[10:13], v[118:121]
	v_mfma_f32_16x16x32_bf16 v[122:125], v[142:145], v[10:13], v[122:125]
	ds_read_b128 v[130:133], v0 offset:256
	ds_read_b128 v[134:137], v0 offset:8448
	ds_read_b128 v[138:141], v0 offset:16640
	ds_read_b128 v[142:145], v0 offset:24832
	v_add_u32_e32 v0, v187, v186
	s_waitcnt lgkmcnt(4)
	v_mfma_f32_16x16x32_bf16 v[126:129], v[146:149], v[26:29], v[126:129]
	v_mfma_f32_16x16x32_bf16 v[114:117], v[150:153], v[26:29], v[114:117]
	v_mfma_f32_16x16x32_bf16 v[118:121], v[230:233], v[26:29], v[118:121]
	v_mfma_f32_16x16x32_bf16 v[122:125], v[234:237], v[26:29], v[122:125]
	ds_read_b128 v[146:149], v1 offset:256
	ds_read_b128 v[150:153], v1 offset:8448
	ds_read_b128 v[230:233], v1 offset:16640
	ds_read_b128 v[234:237], v1 offset:24832
	s_waitcnt lgkmcnt(4)
	v_mfma_f32_16x16x32_bf16 v[126:129], v[130:133], v[22:25], v[126:129]
	v_mfma_f32_16x16x32_bf16 v[114:117], v[134:137], v[22:25], v[114:117]
	v_mfma_f32_16x16x32_bf16 v[118:121], v[138:141], v[22:25], v[118:121]
	ds_read_b128 v[130:133], v229 offset:256
	ds_read_b128 v[134:137], v229 offset:8448
	ds_read_b128 v[138:141], v229 offset:16640
	ds_read_b128 v[238:241], v229 offset:24832
	v_mfma_f32_16x16x32_bf16 v[122:125], v[142:145], v[22:25], v[122:125]
	s_waitcnt lgkmcnt(4)
	v_mfma_f32_16x16x32_bf16 v[126:129], v[146:149], v[14:17], v[126:129]
	v_mfma_f32_16x16x32_bf16 v[114:117], v[150:153], v[14:17], v[114:117]
	v_mfma_f32_16x16x32_bf16 v[118:121], v[230:233], v[14:17], v[118:121]
	v_mfma_f32_16x16x32_bf16 v[122:125], v[234:237], v[14:17], v[122:125]
	s_waitcnt lgkmcnt(0)
	v_mfma_f32_16x16x32_bf16 v[130:133], v[130:133], v[18:21], v[126:129]
	v_mfma_f32_16x16x32_bf16 v[142:145], v[134:137], v[18:21], v[114:117]
	v_mfma_f32_16x16x32_bf16 v[146:149], v[138:141], v[18:21], v[118:121]
	v_mfma_f32_16x16x32_bf16 v[230:233], v[238:241], v[18:21], v[122:125]
	s_nop 0
	v_add_u32_e32 v1, 0x21500, v252
	ds_read_b128 v[150:153], v1
	v_add_u32_e32 v1, 0x21540, v252
	ds_read_b128 v[234:237], v1
	ds_read_b64_tr_b16 v[140:141], v0 offset:1536
	ds_read_b64_tr_b16 v[138:139], v0
	ds_read_b64_tr_b16 v[134:135], v0 offset:32
	ds_read_b64_tr_b16 v[136:137], v0 offset:1568
	ds_read_b64_tr_b16 v[126:127], v0 offset:64
	ds_read_b64_tr_b16 v[128:129], v0 offset:1600
	ds_read_b64_tr_b16 v[118:119], v0 offset:3072
	ds_read_b64_tr_b16 v[120:121], v0 offset:4608
	ds_read_b64_tr_b16 v[114:115], v0 offset:3104
	ds_read_b64_tr_b16 v[116:117], v0 offset:4640
	ds_read_b64_tr_b16 v[122:123], v0 offset:3136
	ds_read_b64_tr_b16 v[124:125], v0 offset:4672
	s_waitcnt lgkmcnt(12)
; DEV unsigned pk2(float lo, float hi) { f32n2 v = {lo, hi}; bf16n2 b = __builtin_convertvector(v, bf16n2); return __builtin_bit_cast(unsigned, b); }
; #define LAS __attribute__((address_space(3)))
; template <int TT>
; DEV void mlstm_a_wave(LAS char* shm, const LAS char* kbuf, const bf16x8 (&qfr)[8], int fr, int fq, float m_prev, const LAS float* tpj, const LAS float* taj, f32x4 (&nacc)[3]) {
;     ...
;     const int t = 16 * TT + fr;
;     const float btm = -fmaxf(m_prev, tpj[t]);
;     f32x4 sm[2 * NK];
; #pragma unroll
;     for (int jj = 0; jj < 2 * NK; ++jj) {
;         if (jj < NT) {
;             const f32x4 a4 = *(const LAS f32x4*)(taj + 16 * jj + 4 * fq);
; #pragma unroll
;             for (int r = 0; r < 4; ++r) {
;                 const int s_ = 16 * jj + 4 * fq + r;
;                 sm[jj][r] = (jj < TT || s_ <= t) ? sacc[jj < NT ? jj : 0][r] * __expf(btm + a4[r]) : 0.f;
;             }
;         } else sm[jj] = (f32x4){0.f, 0.f, 0.f, 0.f};
;     }
; #pragma unroll
;     for (int kk = 0; kk < NK; ++kk) {
;         const u32x4 u = (u32x4){pk2(sm[2 * kk][0], sm[2 * kk][1]), pk2(sm[2 * kk][2], sm[2 * kk][3]), pk2(sm[2 * kk + 1][0], sm[2 * kk + 1][1]), pk2(sm[2 * kk + 1][2], sm[2 * kk + 1][3])};
;         const bf16x8 af = *(const bf16x8*)&u;
; #pragma unroll
;         for (int vt = 0; vt < 3; ++vt) {
;             bf16x8 bv8; bv8[0] = vlo[kk][vt][0]; bv8[1] = vlo[kk][vt][1]; bv8[2] = vlo[kk][vt][2]; bv8[3] = vlo[kk][vt][3];
;             bv8[4] = vhi[kk][vt][0]; bv8[5] = vhi[kk][vt][1]; bv8[6] = vhi[kk][vt][2]; bv8[7] = vhi[kk][vt][3];
;             nacc[vt] = __builtin_amdgcn_mfma_f32_16x16x32_bf16(af, bv8, nacc[vt], 0, 0, 0);
;         }
;     }
	v_max_f32_e32 v0, v246, v246
	v_max_f32_e32 v229, v227, v0
	s_nop 0
	v_sub_f32_e32 v1, v249, v229
	s_nop 0
	v_sub_f32_e32 v0, v242, v229
	v_mul_f32_e32 v0, 0x3fb8aa3b, v0
	v_exp_f32_e32 v0, v0
	v_mul_f32_e32 v1, 0x3fb8aa3b, v1
	v_exp_f32_e32 v1, v1
	v_mul_f32_e32 v0, v230, v0
	v_cndmask_b32_e64 v230, v0, 0, s[6:7]
	v_sub_f32_e32 v0, v243, v229
	v_mul_f32_e32 v0, 0x3fb8aa3b, v0
	v_exp_f32_e32 v0, v0
	s_nop 0
	v_mul_f32_e32 v0, v231, v0
	v_cndmask_b32_e64 v231, 0, v0, s[8:9]
	v_sub_f32_e32 v0, v244, v229
	v_mul_f32_e32 v0, 0x3fb8aa3b, v0
	v_exp_f32_e32 v0, v0
	s_nop 0
	v_mul_f32_e32 v0, v232, v0
	v_cndmask_b32_e64 v232, v0, 0, s[10:11]
	v_sub_f32_e32 v0, v245, v229
	v_mul_f32_e32 v0, 0x3fb8aa3b, v0
	v_exp_f32_e32 v0, v0
	s_nop 0
	v_mul_f32_e32 v0, v233, v0
	v_cndmask_b32_e64 v233, v0, 0, s[12:13]
	v_sub_f32_e32 v0, v248, v229
	v_mul_f32_e32 v0, 0x3fb8aa3b, v0
	v_exp_f32_e32 v0, v0
	s_nop 0
	v_pk_mul_f32 v[0:1], v[146:147], v[0:1]
	v_sub_f32_e32 v146, v250, v229
	v_sub_f32_e32 v147, v251, v229
	v_mul_f32_e32 v146, 0x3fb8aa3b, v146
	v_mul_f32_e32 v147, 0x3fb8aa3b, v147
	v_exp_f32_e32 v146, v146
	v_exp_f32_e32 v147, v147
	s_nop 0
	v_pk_mul_f32 v[146:147], v[148:149], v[146:147]
	v_sub_f32_e32 v148, v234, v229
	v_sub_f32_e32 v149, v235, v229
	v_mul_f32_e32 v148, 0x3fb8aa3b, v148
	v_mul_f32_e32 v149, 0x3fb8aa3b, v149
	v_exp_f32_e32 v148, v148
	v_exp_f32_e32 v149, v149
	s_nop 0
	v_pk_mul_f32 v[142:143], v[142:143], v[148:149]
	v_sub_f32_e32 v148, v236, v229
	v_sub_f32_e32 v149, v237, v229
	v_mul_f32_e32 v148, 0x3fb8aa3b, v148
	v_mul_f32_e32 v149, 0x3fb8aa3b, v149
	v_exp_f32_e32 v148, v148
	v_exp_f32_e32 v149, v149
	s_nop 0
	v_pk_mul_f32 v[144:145], v[144:145], v[148:149]
	v_sub_f32_e32 v148, v150, v229
	v_sub_f32_e32 v149, v151, v229
	v_mul_f32_e32 v148, 0x3fb8aa3b, v148
	v_mul_f32_e32 v149, 0x3fb8aa3b, v149
	v_exp_f32_e32 v148, v148
	v_exp_f32_e32 v149, v149
	s_nop 0
	v_pk_mul_f32 v[130:131], v[130:131], v[148:149]
	v_sub_f32_e32 v148, v152, v229
	v_sub_f32_e32 v149, v153, v229
	v_mul_f32_e32 v148, 0x3fb8aa3b, v148
	v_mul_f32_e32 v149, 0x3fb8aa3b, v149
	v_exp_f32_e32 v148, v148
	v_exp_f32_e32 v149, v149
	v_cvt_pk_bf16_f32 v130, v130, v131
	v_pk_mul_f32 v[132:133], v[132:133], v[148:149]
	s_nop 0
	v_cvt_pk_bf16_f32 v131, v132, v133
	v_cvt_pk_bf16_f32 v132, v142, v143
	v_cvt_pk_bf16_f32 v133, v144, v145
	s_waitcnt lgkmcnt(0)
	s_nop 1
	v_mfma_f32_16x16x32_bf16 v[138:141], v[130:133], v[138:141], 0
	v_mfma_f32_16x16x32_bf16 v[134:137], v[130:133], v[134:137], 0
	v_mfma_f32_16x16x32_bf16 v[126:129], v[130:133], v[126:129], 0
	v_cvt_pk_bf16_f32 v130, v0, v1
	v_cvt_pk_bf16_f32 v131, v146, v147
	v_cvt_pk_bf16_f32 v132, v230, v231
	v_cvt_pk_bf16_f32 v133, v232, v233
	s_nop 1
	v_mfma_f32_16x16x32_bf16 v[118:121], v[130:133], v[118:121], v[138:141]
	v_mfma_f32_16x16x32_bf16 v[114:117], v[130:133], v[114:117], v[134:137]
	v_mfma_f32_16x16x32_bf16 v[122:125], v[130:133], v[122:125], v[126:129]
; template <int TT>
; DEV void mlstm_a_wave(LAS char* shm, const LAS char* kbuf, const bf16x8 (&qfr)[8], int fr, int fq, float m_prev, const LAS float* tpj, const LAS float* taj, f32x4 (&nacc)[3]) {
;     constexpr int VT = 67584, VRS = 96, NT = TT + 1;
;     const LAS char* kb = kbuf + fr * 512 + ((fq ^ (fr & 3)) << 4);
;     int xo[4];
; #pragma unroll
;     for (int b_ = 0; b_ < 4; ++b_) xo[b_] = ((b_ ^ (fr >> 2)) << 6);
;     ...
;     f32x4 sacc[NT];
; #pragma unroll
;     for (int jj = 0; jj < NT; ++jj) sacc[jj] = (f32x4){0.f, 0.f, 0.f, 0.f};
;     bf16x8 kf[NT];
; #pragma unroll
;     for (int jj = 0; jj < NT; ++jj) kf[jj] = *(const LAS bf16x8*)MLK_ADDR(jj, 0);
; #pragma unroll
;     for (int ks = 0; ks < 8; ++ks) {
;         bf16x8 kn[NT];
; #pragma unroll
;         for (int jj = 0; jj < NT; ++jj) kn[jj] = kf[jj];
;         if (ks < 7) {
; #pragma unroll
;             for (int jj = 0; jj < NT; ++jj) kn[jj] = *(const LAS bf16x8*)MLK_ADDR(jj, ks + 1);
;         }
; #pragma unroll
;         for (int jj = 0; jj < NT; ++jj) sacc[jj] = __builtin_amdgcn_mfma_f32_16x16x32_bf16(kf[jj], qfr[ks], sacc[jj], 0, 0, 0);
; #pragma unroll
;         for (int jj = 0; jj < NT; ++jj) kf[jj] = kn[jj];
;     }
;     ...
;     constexpr int NK = (TT >= 2) ? 2 : 1;
;     s16x4 vlo[NK][3], vhi[NK][3];
; #pragma unroll
;     for (int kk = 0; kk < NK; ++kk)
; #pragma unroll
;         for (int vt = 0; vt < 3; ++vt) {
;             vlo[kk][vt] = __builtin_amdgcn_ds_read_tr16_b64_v4i16((LAS s16x4*)(shm + VT + (32 * kk + 4 * fq + (fr >> 2)) * VRS + (16 * vt + 4 * (fr & 3)) * 2));
;             vhi[kk][vt] = __builtin_amdgcn_ds_read_tr16_b64_v4i16((LAS s16x4*)(shm + VT + (32 * kk + 16 + 4 * fq + (fr >> 2)) * VRS + (16 * vt + 4 * (fr & 3)) * 2));
;         }
;     const int t = 16 * TT + fr;
;     const float btm = -fmaxf(m_prev, tpj[t]);
;     f32x4 sm[2 * NK];
; #pragma unroll
;     for (int jj = 0; jj < 2 * NK; ++jj) {
;         if (jj < NT) {
;             const f32x4 a4 = *(const LAS f32x4*)(taj + 16 * jj + 4 * fq);
; #pragma unroll
;             for (int r = 0; r < 4; ++r) {
;                 const int s_ = 16 * jj + 4 * fq + r;
;                 sm[jj][r] = (jj < TT || s_ <= t) ? sacc[jj < NT ? jj : 0][r] * __expf(btm + a4[r]) : 0.f;
;             }
;         } else sm[jj] = (f32x4){0.f, 0.f, 0.f, 0.f};
;     }
; #pragma unroll
;     for (int kk = 0; kk < NK; ++kk) {
.LBB0_1507:
	s_andn2_b64 vcc, exec, s[0:1]
	s_cbranch_vccnz .LBB0_1509
	s_nop 4
	v_add_u32_e32 v247, s40, v203
	v_add_u32_e32 v247, 0x23580, v247
	ds_read_b32 v246, v247
	v_add_u32_e32 v252, s40, v202
	v_add_u32_e32 v247, 0x21500, v252
	ds_read_b128 v[248:251], v247
	v_add_u32_e32 v247, 0x21540, v252
	ds_read_b128 v[230:233], v247
	v_add_u32_e32 v247, 0x21580, v252
	ds_read_b128 v[234:237], v247
	ds_read_b128 v[114:117], v4 offset:8192
	ds_read_b128 v[118:121], v4 offset:16384
	v_add_u32_e32 v0, v5, v183
	ds_read_b128 v[122:125], v0
	ds_read_b128 v[126:129], v0 offset:8192
	ds_read_b128 v[130:133], v0 offset:16384
	s_waitcnt lgkmcnt(3)
	v_mfma_f32_16x16x32_bf16 v[134:137], v[110:113], v[38:41], 0
	v_add_u32_e32 v1, v5, v184
	ds_read_b128 v[138:141], v1
	ds_read_b128 v[142:145], v1 offset:8192
	ds_read_b128 v[146:149], v1 offset:16384
	v_add_u32_e32 v150, v5, v185
	v_mfma_f32_16x16x32_bf16 v[114:117], v[114:117], v[38:41], 0
	v_mfma_f32_16x16x32_bf16 v[118:121], v[118:121], v[38:41], 0
	s_waitcnt lgkmcnt(3)
	v_mfma_f32_16x16x32_bf16 v[122:125], v[122:125], v[34:37], v[134:137]
	v_mfma_f32_16x16x32_bf16 v[114:117], v[126:129], v[34:37], v[114:117]
	v_mfma_f32_16x16x32_bf16 v[118:121], v[130:133], v[34:37], v[118:121]
	ds_read_b128 v[126:129], v150
	ds_read_b128 v[130:133], v150 offset:8192
	ds_read_b128 v[134:137], v150 offset:16384
	s_waitcnt lgkmcnt(3)
	v_mfma_f32_16x16x32_bf16 v[122:125], v[138:141], v[30:33], v[122:125]
	v_mfma_f32_16x16x32_bf16 v[114:117], v[142:145], v[30:33], v[114:117]
	v_mfma_f32_16x16x32_bf16 v[118:121], v[146:149], v[30:33], v[118:121]
	ds_read_b128 v[138:141], v4 offset:256
	ds_read_b128 v[142:145], v4 offset:8448
	ds_read_b128 v[146:149], v4 offset:16640
	s_waitcnt lgkmcnt(3)
	v_mfma_f32_16x16x32_bf16 v[122:125], v[126:129], v[10:13], v[122:125]
	v_mfma_f32_16x16x32_bf16 v[114:117], v[130:133], v[10:13], v[114:117]
	v_mfma_f32_16x16x32_bf16 v[118:121], v[134:137], v[10:13], v[118:121]
	ds_read_b128 v[126:129], v0 offset:256
	ds_read_b128 v[130:133], v0 offset:8448
	ds_read_b128 v[134:137], v0 offset:16640
	v_add_u32_e32 v0, v187, v186
	s_waitcnt lgkmcnt(3)
	v_mfma_f32_16x16x32_bf16 v[122:125], v[138:141], v[26:29], v[122:125]
	v_mfma_f32_16x16x32_bf16 v[114:117], v[142:145], v[26:29], v[114:117]
	v_mfma_f32_16x16x32_bf16 v[118:121], v[146:149], v[26:29], v[118:121]
	ds_read_b128 v[138:141], v1 offset:256
	ds_read_b128 v[142:145], v1 offset:8448
	ds_read_b128 v[146:149], v1 offset:16640
	s_waitcnt lgkmcnt(3)
	v_mfma_f32_16x16x32_bf16 v[122:125], v[126:129], v[22:25], v[122:125]
	v_mfma_f32_16x16x32_bf16 v[114:117], v[130:133], v[22:25], v[114:117]
	v_mfma_f32_16x16x32_bf16 v[118:121], v[134:137], v[22:25], v[118:121]
	ds_read_b128 v[126:129], v150 offset:256
	ds_read_b128 v[130:133], v150 offset:8448
	ds_read_b128 v[134:137], v150 offset:16640
	s_waitcnt lgkmcnt(3)
	v_mfma_f32_16x16x32_bf16 v[122:125], v[138:141], v[14:17], v[122:125]
	v_mfma_f32_16x16x32_bf16 v[114:117], v[142:145], v[14:17], v[114:117]
	v_mfma_f32_16x16x32_bf16 v[118:121], v[146:149], v[14:17], v[118:121]
	s_waitcnt lgkmcnt(0)
	v_mfma_f32_16x16x32_bf16 v[142:145], v[126:129], v[18:21], v[122:125]
	v_mfma_f32_16x16x32_bf16 v[130:133], v[130:133], v[18:21], v[114:117]
	v_mfma_f32_16x16x32_bf16 v[146:149], v[134:137], v[18:21], v[118:121]
	s_nop 0
	ds_read_b64_tr_b16 v[140:141], v0 offset:1536
	ds_read_b64_tr_b16 v[138:139], v0
	ds_read_b64_tr_b16 v[134:135], v0 offset:32
	ds_read_b64_tr_b16 v[136:137], v0 offset:1568
	ds_read_b64_tr_b16 v[126:127], v0 offset:64
	ds_read_b64_tr_b16 v[128:129], v0 offset:1600
	ds_read_b64_tr_b16 v[118:119], v0 offset:3072
	ds_read_b64_tr_b16 v[120:121], v0 offset:4608
	ds_read_b64_tr_b16 v[114:115], v0 offset:3104
	ds_read_b64_tr_b16 v[116:117], v0 offset:4640
	ds_read_b64_tr_b16 v[122:123], v0 offset:3136
	ds_read_b64_tr_b16 v[124:125], v0 offset:4672
	s_waitcnt lgkmcnt(12)
	v_max_f32_e32 v0, v246, v246
	v_max_f32_e32 v229, v227, v0
	s_nop 0
	v_sub_f32_e32 v0, v234, v229
	v_mul_f32_e32 v0, 0x3fb8aa3b, v0
	v_exp_f32_e32 v0, v0
	v_sub_f32_e32 v1, v237, v229
	v_mul_f32_e32 v1, 0x3fb8aa3b, v1
	v_exp_f32_e32 v1, v1
	v_mul_f32_e32 v0, v146, v0
	v_cndmask_b32_e64 v234, v0, 0, s[6:7]
	v_sub_f32_e32 v0, v235, v229
	v_mul_f32_e32 v0, 0x3fb8aa3b, v0
	v_exp_f32_e32 v0, v0
	v_sub_f32_e32 v146, v248, v229
	v_mul_f32_e32 v146, 0x3fb8aa3b, v146
	v_exp_f32_e32 v146, v146
	v_mul_f32_e32 v0, v147, v0
	v_sub_f32_e32 v147, v249, v229
	v_mul_f32_e32 v147, 0x3fb8aa3b, v147
	v_exp_f32_e32 v147, v147
	v_cndmask_b32_e64 v235, v0, 0, s[14:15]
	v_sub_f32_e32 v0, v236, v229
	v_mul_f32_e32 v0, 0x3fb8aa3b, v0
	v_pk_mul_f32 v[142:143], v[142:143], v[146:147]
	v_sub_f32_e32 v146, v250, v229
	v_sub_f32_e32 v147, v251, v229
	v_mul_f32_e32 v146, 0x3fb8aa3b, v146
	v_mul_f32_e32 v147, 0x3fb8aa3b, v147
	v_exp_f32_e32 v146, v146
	v_exp_f32_e32 v147, v147
	v_exp_f32_e32 v0, v0
	v_pk_mul_f32 v[144:145], v[144:145], v[146:147]
	v_sub_f32_e32 v146, v230, v229
	v_sub_f32_e32 v147, v231, v229
	v_mul_f32_e32 v146, 0x3fb8aa3b, v146
	v_mul_f32_e32 v147, 0x3fb8aa3b, v147
	v_exp_f32_e32 v146, v146
	v_exp_f32_e32 v147, v147
	v_pk_mul_f32 v[0:1], v[148:149], v[0:1]
	v_pk_mul_f32 v[146:147], v[130:131], v[146:147]
	v_sub_f32_e32 v130, v232, v229
	v_sub_f32_e32 v131, v233, v229
	v_mul_f32_e32 v130, 0x3fb8aa3b, v130
	v_mul_f32_e32 v131, 0x3fb8aa3b, v131
	v_exp_f32_e32 v130, v130
	v_exp_f32_e32 v131, v131
	v_cvt_pk_bf16_f32 v0, v0, v1
	v_cndmask_b32_e64 v1, v0, 0, s[18:19]
	v_lshrrev_b32_e32 v0, 16, v0
	v_pk_mul_f32 v[148:149], v[132:133], v[130:131]
	v_cvt_pk_bf16_f32 v130, v142, v143
	v_cvt_pk_bf16_f32 v131, v144, v145
	v_cvt_pk_bf16_f32 v132, v146, v147
	v_cvt_pk_bf16_f32 v133, v148, v149
	v_cndmask_b32_e64 v0, v0, 0, s[16:17]
	s_waitcnt lgkmcnt(0)
	s_nop 0
	v_mfma_f32_16x16x32_bf16 v[138:141], v[130:133], v[138:141], 0
	v_mfma_f32_16x16x32_bf16 v[134:137], v[130:133], v[134:137], 0
	v_mfma_f32_16x16x32_bf16 v[126:129], v[130:133], v[126:129], 0
	v_cvt_pk_bf16_f32 v130, v234, v235
	v_perm_b32 v131, v0, v1, s60
	v_mov_b32_e32 v132, v3
	v_mov_b32_e32 v133, v3
	s_nop 1
	v_mfma_f32_16x16x32_bf16 v[118:121], v[130:133], v[118:121], v[138:141]
	v_mfma_f32_16x16x32_bf16 v[114:117], v[130:133], v[114:117], v[134:137]
	v_mfma_f32_16x16x32_bf16 v[122:125], v[130:133], v[122:125], v[126:129]
